# v14 plus nt cache policy on the once-read GLA pass-3 row loads in P4
# speedup vs baseline: 1.0159x; 1.0002x over previous
.LBB0_928:
	s_or_b64 exec, exec, s[8:9]
	s_waitcnt lgkmcnt(0)
	s_barrier
	ds_read_b32 v0, v72
	s_mov_b64 s[8:9], -1
	s_waitcnt lgkmcnt(0)
	s_barrier
	v_cmp_lt_i32_e32 vcc, s28, v0
	v_readfirstlane_b32 s48, v0
	s_cbranch_vccnz .LBB0_923
	s_lshl_b32 s16, s48, 2
	s_cmp_eq_u32 s16, 0x7ffffffc
	s_cbranch_scc1 .LBB0_922
	s_cmpk_gt_i32 s16, 0x7ff
	s_cselect_b64 s[18:19], -1, 0
	s_cmpk_lt_i32 s16, 0x800
	s_cselect_b64 s[20:21], -1, 0
	s_and_b64 s[8:9], s[20:21], exec
	s_cselect_b32 s12, 64, 16
	s_ashr_i32 s17, s16, 31
	s_lshl_b64 s[8:9], s[16:17], 14
	v_lshl_add_u64 v[0:1], v[60:61], 0, s[8:9]
	v_mov_b32_e32 v78, v186
	v_add_co_u32_e32 v2, vcc, 0x2000, v0
	v_mov_b32_e32 v18, v16
	s_nop 0
	v_addc_co_u32_e32 v3, vcc, 0, v1, vcc
	global_load_dwordx4 v[20:23], v[0:1], off nt
	global_load_dwordx4 v[24:27], v[2:3], off nt
	v_mov_b32_e32 v19, v16
	v_mov_b32_e32 v17, v16
	v_mov_b64_e32 v[50:51], v[18:19]
	v_mov_b64_e32 v[58:59], v[18:19]
	s_waitcnt vmcnt(5)
	v_mov_b64_e32 v[30:31], v[18:19]
	s_waitcnt vmcnt(4)
	v_mov_b64_e32 v[34:35], v[18:19]
	v_cmp_gt_i32_e32 vcc, s12, v63
	v_mov_b64_e32 v[48:49], v[16:17]
	v_mov_b64_e32 v[56:57], v[16:17]
	v_mov_b64_e32 v[28:29], v[16:17]
	v_mov_b64_e32 v[32:33], v[16:17]
	s_and_saveexec_b64 s[8:9], vcc
	s_cbranch_execz .LBB0_932
	s_lshl_b32 s12, s48, 4
	s_and_b32 s12, s12, 0x180
	s_and_b64 s[22:23], s[20:21], exec
	s_cselect_b32 s12, s12, 0
	s_lshl_b32 s22, s48, 6
	s_lshl_b32 s23, s48, 8
	s_and_b32 s22, s22, 0xfffff800
	s_and_b32 s23, s23, 0x700
	s_or_b32 s24, s22, s23
	s_and_b64 s[22:23], s[20:21], exec
	s_cselect_b32 s22, s24, 0x8200
	v_add_u32_e32 v2, s22, v63
	v_mov_b64_e32 v[0:1], s[10:11]
	v_mad_i64_i32 v[0:1], s[22:23], v2, s29, v[0:1]
	s_lshl_b32 s12, s12, 1
	v_lshl_add_u64 v[0:1], v[0:1], 0, s[12:13]
	v_mov_b32_e32 v67, v16
	v_lshl_add_u64 v[0:1], v[0:1], 0, v[66:67]
	global_load_dwordx4 v[28:31], v[0:1], off offset:1040 nt
	global_load_dwordx4 v[32:35], v[0:1], off offset:1024 nt
	global_load_dwordx4 v[48:51], v[0:1], off offset:2064 nt
	global_load_dwordx4 v[56:59], v[0:1], off offset:2048 nt

.LBB0_936:
	s_lshl_b64 s[20:21], s[16:17], 13
	v_lshl_add_u64 v[0:1], s[20:21], 1, v[64:65]
	v_add_co_u32_e32 v2, vcc, 0x2000, v0
	s_nop 1
	v_addc_co_u32_e32 v3, vcc, 0, v1, vcc
	global_load_dwordx4 v[40:43], v[0:1], off nt
	global_load_dwordx4 v[36:39], v[2:3], off nt
	s_mov_b64 s[20:21], -1
	s_and_b64 vcc, exec, s[18:19]
	s_cbranch_vccz .LBB0_934

.LBB0_947:
	s_ashr_i32 s19, s18, 31
	s_lshl_b64 s[50:51], s[18:19], 14
	v_lshl_add_u64 v[0:1], v[60:61], 0, s[50:51]
	v_add_co_u32_e32 v2, vcc, 0x2000, v0
	v_mov_b32_e32 v18, v16
	s_nop 0
	v_addc_co_u32_e32 v3, vcc, 0, v1, vcc
	global_load_dwordx4 v[20:23], v[0:1], off nt
	global_load_dwordx4 v[24:27], v[2:3], off nt
	v_mov_b32_e32 v19, v16
	v_mov_b32_e32 v17, v16
	v_mov_b64_e32 v[46:47], v[18:19]
	v_mov_b64_e32 v[54:55], v[18:19]
	v_mov_b64_e32 v[30:31], v[18:19]
	v_mov_b64_e32 v[34:35], v[18:19]
	v_cmp_gt_i32_e32 vcc, s24, v63
	v_mov_b64_e32 v[44:45], v[16:17]
	v_mov_b64_e32 v[52:53], v[16:17]
	v_mov_b64_e32 v[28:29], v[16:17]
	v_mov_b64_e32 v[32:33], v[16:17]
	s_and_saveexec_b64 s[24:25], vcc
	s_cbranch_execz .LBB0_949
	v_add_u32_e32 v2, s47, v63
	v_mov_b64_e32 v[0:1], s[10:11]
	v_mad_i64_i32 v[0:1], s[50:51], v2, s29, v[0:1]
	s_lshl_b32 s12, s12, 8
	v_lshl_add_u64 v[0:1], v[0:1], 0, s[12:13]
	v_mov_b32_e32 v67, v16
	v_lshl_add_u64 v[0:1], v[0:1], 0, v[66:67]
	global_load_dwordx4 v[28:31], v[0:1], off offset:1040 nt
	global_load_dwordx4 v[32:35], v[0:1], off offset:1024 nt
	global_load_dwordx4 v[44:47], v[0:1], off offset:2064 nt
	global_load_dwordx4 v[52:55], v[0:1], off offset:2048 nt
.LBB0_949:
	s_or_b64 exec, exec, s[24:25]
	v_mov_b32_e32 v39, 0
	s_andn2_b64 vcc, exec, s[22:23]
	v_mov_b32_e32 v38, 0
	v_mov_b32_e32 v37, 0
	v_mov_b32_e32 v36, 0
	v_mov_b32_e32 v43, 0
	v_mov_b32_e32 v42, 0
	v_mov_b32_e32 v41, 0
	v_mov_b32_e32 v40, 0
	s_cbranch_vccnz .LBB0_951
	s_lshl_b64 s[22:23], s[18:19], 13
	v_lshl_add_u64 v[0:1], s[22:23], 1, v[64:65]
	v_add_co_u32_e32 v2, vcc, 0x2000, v0
	s_nop 1
	v_addc_co_u32_e32 v3, vcc, 0, v1, vcc
	global_load_dwordx4 v[40:43], v[0:1], off nt
	global_load_dwordx4 v[36:39], v[2:3], off nt

.LBB0_969:
	s_ashr_i32 s21, s20, 31
	s_lshl_b64 s[50:51], s[20:21], 14
	v_lshl_add_u64 v[0:1], v[60:61], 0, s[50:51]
	v_add_co_u32_e32 v2, vcc, 0x2000, v0
	s_waitcnt lgkmcnt(4)
	v_mov_b32_e32 v18, v16
	v_addc_co_u32_e32 v3, vcc, 0, v1, vcc
	global_load_dwordx4 v[20:23], v[0:1], off nt
	global_load_dwordx4 v[24:27], v[2:3], off nt
	v_mov_b32_e32 v19, v16
	v_mov_b32_e32 v17, v16
	v_mov_b64_e32 v[50:51], v[18:19]
	v_mov_b64_e32 v[58:59], v[18:19]
	v_mov_b64_e32 v[30:31], v[18:19]
	v_mov_b64_e32 v[34:35], v[18:19]
	v_cmp_gt_i32_e32 vcc, s22, v63
	v_mov_b64_e32 v[48:49], v[16:17]
	v_mov_b64_e32 v[56:57], v[16:17]
	v_mov_b64_e32 v[28:29], v[16:17]
	v_mov_b64_e32 v[32:33], v[16:17]
	s_and_saveexec_b64 s[22:23], vcc
	s_cbranch_execz .LBB0_971
	v_add_u32_e32 v2, s46, v63
	v_mov_b64_e32 v[0:1], s[10:11]
	v_mad_i64_i32 v[0:1], s[46:47], v2, s29, v[0:1]
	s_lshl_b32 s12, s12, 8
	v_lshl_add_u64 v[0:1], v[0:1], 0, s[12:13]
	v_mov_b32_e32 v67, v16
	v_lshl_add_u64 v[0:1], v[0:1], 0, v[66:67]
	global_load_dwordx4 v[28:31], v[0:1], off offset:1040 nt
	global_load_dwordx4 v[32:35], v[0:1], off offset:1024 nt
	global_load_dwordx4 v[48:51], v[0:1], off offset:2064 nt
	global_load_dwordx4 v[56:59], v[0:1], off offset:2048 nt
.LBB0_971:
	s_or_b64 exec, exec, s[22:23]
	v_mov_b32_e32 v39, 0
	s_andn2_b64 vcc, exec, s[18:19]
	v_mov_b32_e32 v38, 0
	v_mov_b32_e32 v37, 0
	v_mov_b32_e32 v36, 0
	v_mov_b32_e32 v43, 0
	v_mov_b32_e32 v42, 0
	v_mov_b32_e32 v41, 0
	v_mov_b32_e32 v40, 0
	s_cbranch_vccnz .LBB0_973
	s_lshl_b64 s[18:19], s[20:21], 13
	v_lshl_add_u64 v[0:1], s[18:19], 1, v[64:65]
	v_add_co_u32_e32 v2, vcc, 0x2000, v0
	s_nop 1
	v_addc_co_u32_e32 v3, vcc, 0, v1, vcc
	global_load_dwordx4 v[40:43], v[0:1], off nt
	global_load_dwordx4 v[36:39], v[2:3], off nt

.LBB0_990:
	s_ashr_i32 s19, s18, 31
	s_lshl_b64 s[46:47], s[18:19], 14
	v_lshl_add_u64 v[0:1], v[60:61], 0, s[46:47]
	v_add_co_u32_e32 v2, vcc, 0x2000, v0
	s_waitcnt lgkmcnt(4)
	v_mov_b32_e32 v18, v16
	v_addc_co_u32_e32 v3, vcc, 0, v1, vcc
	global_load_dwordx4 v[20:23], v[0:1], off nt
	global_load_dwordx4 v[24:27], v[2:3], off nt
	v_mov_b32_e32 v19, v16
	v_mov_b32_e32 v17, v16
	v_mov_b64_e32 v[46:47], v[18:19]
	v_mov_b64_e32 v[54:55], v[18:19]
	v_mov_b64_e32 v[30:31], v[18:19]
	v_mov_b64_e32 v[34:35], v[18:19]
	v_cmp_gt_i32_e32 vcc, s22, v63
	v_mov_b64_e32 v[44:45], v[16:17]
	v_mov_b64_e32 v[52:53], v[16:17]
	v_mov_b64_e32 v[28:29], v[16:17]
	v_mov_b64_e32 v[32:33], v[16:17]
	s_and_saveexec_b64 s[22:23], vcc
	s_cbranch_execz .LBB0_992
	v_add_u32_e32 v2, s17, v63
	v_mov_b64_e32 v[0:1], s[10:11]
	v_mad_i64_i32 v[0:1], s[46:47], v2, s29, v[0:1]
	s_lshl_b32 s12, s12, 8
	v_lshl_add_u64 v[0:1], v[0:1], 0, s[12:13]
	v_mov_b32_e32 v67, v16
	v_lshl_add_u64 v[0:1], v[0:1], 0, v[66:67]
	global_load_dwordx4 v[28:31], v[0:1], off offset:1040 nt
	global_load_dwordx4 v[32:35], v[0:1], off offset:1024 nt
	global_load_dwordx4 v[44:47], v[0:1], off offset:2064 nt
	global_load_dwordx4 v[52:55], v[0:1], off offset:2048 nt
.LBB0_992:
	s_or_b64 exec, exec, s[22:23]
	v_mov_b32_e32 v39, 0
	s_andn2_b64 vcc, exec, s[20:21]
	v_mov_b32_e32 v38, 0
	v_mov_b32_e32 v37, 0
	v_mov_b32_e32 v36, 0
	v_mov_b32_e32 v43, 0
	v_mov_b32_e32 v42, 0
	v_mov_b32_e32 v41, 0
	v_mov_b32_e32 v40, 0
	s_cbranch_vccnz .LBB0_994
	s_lshl_b64 s[20:21], s[18:19], 13
	v_lshl_add_u64 v[0:1], s[20:21], 1, v[64:65]
	v_add_co_u32_e32 v2, vcc, 0x2000, v0
	s_nop 1
	v_addc_co_u32_e32 v3, vcc, 0, v1, vcc
	global_load_dwordx4 v[40:43], v[0:1], off nt
	global_load_dwordx4 v[36:39], v[2:3], off nt
